# speedup vs baseline: 1.0102x; 1.0042x over previous
.LBB0_504:
	v_cvt_f32_i32_e32 v1, s59
	v_ashrrev_i32_e32 v61, 3, v0
	v_lshlrev_b32_e32 v0, 3, v0
	v_and_b32_e32 v60, 56, v0
	v_cvt_f32_i32_e32 v0, s53
	v_rcp_iflag_f32_e32 v2, v1
	s_xor_b32 s2, s53, s59
	s_ashr_i32 s2, s2, 30
	s_or_b32 s42, s2, 1
	v_mul_f32_e32 v2, v0, v2
	v_trunc_f32_e32 v2, v2
	v_fma_f32 v0, -v2, v1, v0
	v_cvt_i32_f32_e32 v2, v2
	v_cmp_ge_f32_e64 s[2:3], |v0|, |v1|
	s_and_b64 s[2:3], s[2:3], exec
	s_cselect_b32 s2, s42, 0
	v_add_u32_e32 v0, s2, v2
	v_bfe_i32 v64, v0, 0, 16
	v_mul_lo_u32 v0, s59, v64
	v_sub_u32_e32 v65, s53, v0
	v_lshl_add_u32 v0, v64, 6, v61
	v_ashrrev_i32_e32 v3, 31, v0
	v_mad_u64_u32 v[0:1], s[2:3], v0, s47, 0
	v_mov_b32_e32 v2, v1
	v_mad_u64_u32 v[2:3], s[2:3], v3, s47, v[2:3]
	v_mov_b32_e32 v1, v2
	v_lshlrev_b32_e32 v2, 8, v65
	v_lshl_add_u64 v[0:1], v[0:1], 2, s[40:41]
	v_ashrrev_i32_e32 v3, 31, v2
	v_lshl_add_u64 v[0:1], v[2:3], 2, v[0:1]
	v_lshlrev_b32_e32 v128, 2, v60
	v_lshl_add_u64 v[24:25], v[0:1], 0, v[128:129]
	global_load_dwordx4 v[0:3], v[24:25], off nt
	global_load_dwordx4 v[4:7], v[24:25], off offset:16 nt
	global_load_dwordx4 v[8:11], v[24:25], off offset:768 nt
	global_load_dwordx4 v[28:31], v[24:25], off offset:784 nt
	global_load_dwordx4 v[12:15], v[24:25], off offset:256 nt
	global_load_dwordx4 v[16:19], v[24:25], off offset:272 nt
	global_load_dwordx4 v[20:23], v[24:25], off offset:512 nt
	s_nop 0
	global_load_dwordx4 v[24:27], v[24:25], off offset:528 nt
	s_movk_i32 s2, 0x104
	v_mul_lo_u32 v32, v61, s2
	v_lshlrev_b32_e32 v33, 8, v61
	v_sub_u32_e32 v33, v32, v33
	v_mul_u32_u24_e32 v34, 0x104, v60
	s_lshl_b32 s2, s44, 1
	v_readlane_b32 s3, v254, 62
	v_add_u32_e32 v62, v32, v128
	v_add_u32_e32 v63, v33, v34
	s_sub_i32 s42, 0x100, s44
	s_xor_b64 s[58:59], s[34:35], -1
	s_sub_i32 s43, s3, s2
	v_lshlrev_b32_e32 v128, 1, v60
	s_waitcnt vmcnt(4)
	v_mov_b32_e32 v69, v28
	v_mov_b32_e32 v68, v29
	v_mov_b32_e32 v67, v30
	v_mov_b32_e32 v66, v31
	s_waitcnt vmcnt(0)
	s_branch .LBB0_506

.LBB0_506:
	s_add_i32 s2, s82, -1
	s_lshr_b32 s2, s2, 3
	s_mov_b32 s4, 0xd011915
	s_mov_b32 s5, 0xffff11
	s_cmp_eq_u32 s2, 1
	s_cselect_b32 s4, 0x8041a16, s4
	s_cselect_b32 s5, 0x120f0e, s5
	s_cmp_eq_u32 s2, 2
	s_cselect_b32 s4, 0x13051b17, s4
	s_cselect_b32 s5, 0xffffff, s5
	s_sub_i32 s2, s45, s44
	s_add_i32 s45, s2, 0x100
	s_cmp_lt_i32 s43, s46
	s_cselect_b64 s[54:55], -1, 0
	s_cmp_ge_i32 s43, s46
	s_cbranch_scc1 .LBB0_520
	s_movk_i32 s35, 0x180
	s_bfe_u32 s34, s4, 0x80000
	s_lshr_b32 s62, s34, 2
	s_cmp_lt_i32 s62, 1
	s_cbranch_scc1 .LBB0_512
	s_cmp_eq_u32 s62, 1
	s_mov_b64 s[2:3], -1
	s_cbranch_scc1 .LBB0_510
	s_and_b32 s2, s34, 0xf8
	s_cmp_eq_u32 s62, 4
	s_movk_i32 s3, 0x400
	s_cselect_b32 s3, 0x100, s3
	s_cmp_lg_u32 s2, 8
	s_cselect_b32 s35, s3, 0x80
	s_mov_b64 s[2:3], 0

.LBB0_512:
	s_cmp_lt_i32 s43, s35
	s_cselect_b64 s[2:3], -1, 0
	s_and_b64 vcc, exec, s[2:3]
	s_cselect_b32 s35, 0, s35
	s_sub_i32 s53, s43, s35
	s_cbranch_vccnz .LBB0_521
	s_movk_i32 s61, 0x180
	s_bfe_u32 s60, s4, 0x80008
	s_lshr_b32 s34, s60, 2
	s_cmp_lt_i32 s34, 1
	s_cbranch_scc1 .LBB0_518
	s_cmp_lg_u32 s34, 1
	s_mov_b64 s[2:3], -1
	s_cbranch_scc0 .LBB0_516
	s_and_b32 s2, s60, 0xf8
	s_cmp_eq_u32 s34, 4
	s_movk_i32 s3, 0x400
	s_cselect_b32 s3, 0x100, s3
	s_cmp_lg_u32 s2, 8
	s_cselect_b32 s61, s3, 0x80
	s_mov_b64 s[2:3], 0

.LBB0_522:
	s_movk_i32 s61, 0x180
	s_bfe_u32 s35, s4, 0x80010
	s_lshr_b32 s34, s35, 2
	s_cmp_lt_i32 s34, 1
	s_cbranch_scc1 .LBB0_527
	s_cmp_lg_u32 s34, 1
	s_mov_b64 s[2:3], -1
	s_cbranch_scc0 .LBB0_525
	s_and_b32 s2, s35, 0xf8
	s_cmp_eq_u32 s34, 4
	s_movk_i32 s3, 0x400
	s_cselect_b32 s3, 0x100, s3
	s_cmp_lg_u32 s2, 8
	s_cselect_b32 s61, s3, 0x80
	s_mov_b64 s[2:3], 0

.LBB0_528:
	s_movk_i32 s61, 0x180
	s_bfe_u32 s35, s4, 0x80018
	s_lshr_b32 s34, s35, 2
	s_cmp_lt_i32 s34, 1
	s_cbranch_scc1 .LBB0_533
	s_cmp_lg_u32 s34, 1
	s_mov_b64 s[2:3], -1
	s_cbranch_scc0 .LBB0_531
	s_and_b32 s2, s35, 0xf8
	s_cmp_eq_u32 s34, 4
	s_movk_i32 s3, 0x400
	s_cselect_b32 s3, 0x100, s3
	s_cmp_lg_u32 s2, 8
	s_cselect_b32 s61, s3, 0x80
	s_mov_b64 s[2:3], 0

.LBB0_534:
	s_cmp_gt_i32 s62, -1
	s_cselect_b64 s[2:3], -1, 0
	s_or_b64 s[2:3], s[58:59], s[2:3]
	s_and_b64 vcc, exec, s[2:3]
	s_cbranch_vccnz .LBB0_541
	s_movk_i32 s61, 0x180
	s_bfe_u32 s35, s5, 0x80000
	s_lshr_b32 s34, s35, 2
	s_cmp_lt_i32 s34, 1
	s_cbranch_scc1 .LBB0_540
	s_cmp_lg_u32 s34, 1
	s_mov_b64 s[2:3], -1
	s_cbranch_scc0 .LBB0_538
	s_and_b32 s2, s35, 0xf8
	s_cmp_eq_u32 s34, 4
	s_movk_i32 s3, 0x400
	s_cselect_b32 s3, 0x100, s3
	s_cmp_lg_u32 s2, 8
	s_cselect_b32 s61, s3, 0x80
	s_mov_b64 s[2:3], 0

.LBB0_541:
	s_cmp_gt_i32 s62, -1
	s_cselect_b64 s[2:3], -1, 0
	s_or_b64 s[2:3], s[0:1], s[2:3]
	s_and_b64 vcc, exec, s[2:3]
	s_cbranch_vccnz .LBB0_548
	s_movk_i32 s61, 0x180
	s_bfe_u32 s35, s5, 0x80008
	s_lshr_b32 s34, s35, 2
	s_cmp_lt_i32 s34, 1
	s_cbranch_scc1 .LBB0_547
	s_cmp_lg_u32 s34, 1
	s_mov_b64 s[2:3], -1
	s_cbranch_scc0 .LBB0_545
	s_and_b32 s2, s35, 0xf8
	s_cmp_eq_u32 s34, 4
	s_movk_i32 s3, 0x400
	s_cselect_b32 s3, 0x100, s3
	s_cmp_lg_u32 s2, 8
	s_cselect_b32 s61, s3, 0x80
	s_mov_b64 s[2:3], 0

.LBB0_548:
	s_cmp_gt_i32 s62, -1
	s_cselect_b64 s[2:3], -1, 0
	s_or_b64 s[2:3], s[0:1], s[2:3]
	s_and_b64 vcc, exec, s[2:3]
	s_cbranch_vccnz .LBB0_555
	s_movk_i32 s61, 0x180
	s_bfe_u32 s35, s5, 0x80010
	s_lshr_b32 s34, s35, 2
	s_cmp_lt_i32 s34, 1
	s_cbranch_scc1 .LBB0_554
	s_cmp_lg_u32 s34, 1
	s_mov_b64 s[2:3], -1
	s_cbranch_scc0 .LBB0_552
	s_and_b32 s2, s35, 0xf8
	s_cmp_eq_u32 s34, 4
	s_movk_i32 s3, 0x400
	s_cselect_b32 s3, 0x100, s3
	s_cmp_lg_u32 s2, 8
	s_cselect_b32 s61, s3, 0x80
	s_mov_b64 s[2:3], 0

.LBB0_578:
	s_barrier
	ds_write2_b32 v62, v0, v1 offset1:1
	ds_write2_b32 v62, v2, v3 offset0:2 offset1:3
	ds_write2_b32 v62, v4, v5 offset0:4 offset1:5
	ds_write2_b32 v62, v6, v7 offset0:6 offset1:7
	v_add_u32_e32 v0, 0x4100, v62
	ds_write2_b32 v0, v12, v13 offset1:1
	v_add_u32_e32 v0, 0x4108, v62
	ds_write2_b32 v0, v14, v15 offset1:1
	v_add_u32_e32 v0, 0x4110, v62
	ds_write2_b32 v0, v16, v17 offset1:1
	v_add_u32_e32 v0, 0x4118, v62
	ds_write2_b32 v0, v18, v19 offset1:1
	v_add_u32_e32 v0, 0x8200, v62
	ds_write2_b32 v0, v20, v21 offset1:1
	v_add_u32_e32 v0, 0x8208, v62
	ds_write2_b32 v0, v22, v23 offset1:1
	v_add_u32_e32 v0, 0x8210, v62
	ds_write2_b32 v0, v24, v25 offset1:1
	v_add_u32_e32 v0, 0x8218, v62
	ds_write2_b32 v0, v26, v27 offset1:1
	v_add_u32_e32 v0, 0xc300, v62
	ds_write2_b32 v0, v8, v9 offset1:1
	v_add_u32_e32 v0, 0xc308, v62
	ds_write2_b32 v0, v10, v11 offset1:1
	v_add_u32_e32 v0, 0xc310, v62
	ds_write2_b32 v0, v69, v68 offset1:1
	v_add_u32_e32 v0, 0xc318, v62
	ds_write2_b32 v0, v67, v66 offset1:1
	s_waitcnt lgkmcnt(0)
	s_barrier
	ds_read2_b32 v[2:3], v63 offset1:65
	ds_read2_b32 v[4:5], v63 offset0:130 offset1:195
	v_lshlrev_b32_e32 v0, 6, v64
	v_add_u32_e32 v8, 0x400, v63
	v_ashrrev_i32_e32 v1, 31, v0
	ds_read2_b32 v[6:7], v8 offset0:4 offset1:69
	ds_read2_b32 v[8:9], v8 offset0:134 offset1:199
	v_lshlrev_b64 v[0:1], 1, v[0:1]
	v_lshl_add_u32 v12, v65, 8, v61
	v_lshl_add_u64 v[0:1], s[50:51], 0, v[0:1]
	v_lshl_add_u64 v[10:11], v[0:1], 0, v[128:129]
	s_waitcnt lgkmcnt(2)
	v_cvt_pk_bf16_f32 v1, v4, v5
	v_mad_i64_i32 v[4:5], s[2:3], v12, s52, 0
	v_cvt_pk_bf16_f32 v0, v2, v3
	s_waitcnt lgkmcnt(1)
	v_cvt_pk_bf16_f32 v2, v6, v7
	v_lshl_add_u64 v[4:5], v[4:5], 1, v[10:11]
	s_waitcnt lgkmcnt(0)
	v_cvt_pk_bf16_f32 v3, v8, v9
	v_add_u32_e32 v6, 0x4600, v63
	global_store_dwordx4 v[4:5], v[0:3], off sc1
	s_nop 1
	v_add_u32_e32 v0, 0x4000, v63
	v_add_u32_e32 v2, 0x4200, v63
	v_add_u32_e32 v4, 0x4400, v63
	ds_read2_b32 v[0:1], v0 offset0:64 offset1:129
	ds_read2_b32 v[2:3], v2 offset0:66 offset1:131
	ds_read2_b32 v[4:5], v4 offset0:68 offset1:133
	s_waitcnt lgkmcnt(2)
	v_cvt_pk_bf16_f32 v0, v0, v1
	s_waitcnt lgkmcnt(1)
	v_cvt_pk_bf16_f32 v1, v2, v3
	s_waitcnt lgkmcnt(0)
	v_cvt_pk_bf16_f32 v2, v4, v5
	v_add_u32_e32 v4, 64, v12
	v_mad_i64_i32 v[4:5], s[2:3], v4, s52, 0
	v_lshl_add_u64 v[4:5], v[4:5], 1, v[10:11]
	ds_read2_b32 v[6:7], v6 offset0:70 offset1:135
	s_waitcnt lgkmcnt(0)
	v_cvt_pk_bf16_f32 v3, v6, v7
	v_add_u32_e32 v6, 0x8800, v63
	global_store_dwordx4 v[4:5], v[0:3], off sc1
	s_nop 1
	v_add_u32_e32 v0, 0x8000, v63
	v_add_u32_e32 v4, 0x8400, v63
	ds_read2_b32 v[0:1], v0 offset0:128 offset1:193
	ds_read2_b32 v[2:3], v4 offset0:2 offset1:67
	ds_read2_b32 v[4:5], v4 offset0:132 offset1:197
	s_waitcnt lgkmcnt(2)
	v_cvt_pk_bf16_f32 v0, v0, v1
	s_waitcnt lgkmcnt(1)
	v_cvt_pk_bf16_f32 v1, v2, v3
	s_waitcnt lgkmcnt(0)
	v_cvt_pk_bf16_f32 v2, v4, v5
	v_add_u32_e32 v4, 0x80, v12
	v_mad_i64_i32 v[4:5], s[2:3], v4, s52, 0
	v_lshl_add_u64 v[4:5], v[4:5], 1, v[10:11]
	ds_read2_b32 v[6:7], v6 offset0:6 offset1:71
	s_waitcnt lgkmcnt(0)
	v_cvt_pk_bf16_f32 v3, v6, v7
	v_add_u32_e32 v6, 0xc800, v63
	global_store_dwordx4 v[4:5], v[0:3], off sc1
	s_nop 1
	v_add_u32_e32 v0, 0xc200, v63
	v_add_u32_e32 v2, 0xc400, v63
	v_add_u32_e32 v4, 0xc600, v63
	ds_read2_b32 v[0:1], v0 offset0:64 offset1:129
	ds_read2_b32 v[2:3], v2 offset0:66 offset1:131
	ds_read2_b32 v[4:5], v4 offset0:68 offset1:133
	s_waitcnt lgkmcnt(2)
	v_cvt_pk_bf16_f32 v0, v0, v1
	s_waitcnt lgkmcnt(1)
	v_cvt_pk_bf16_f32 v1, v2, v3
	s_waitcnt lgkmcnt(0)
	v_cvt_pk_bf16_f32 v2, v4, v5
	v_add_u32_e32 v4, 0xc0, v12
	v_mad_i64_i32 v[4:5], s[2:3], v4, s52, 0
	ds_read2_b32 v[6:7], v6 offset0:70 offset1:135
	s_waitcnt lgkmcnt(0)
	v_cvt_pk_bf16_f32 v3, v6, v7
	v_lshl_add_u64 v[4:5], v[4:5], 1, v[10:11]
	global_store_dwordx4 v[4:5], v[0:3], off sc1
	s_nop 1
	s_andn2_b64 vcc, exec, s[54:55]
	s_mov_b64 s[2:3], -1
	s_cbranch_vccnz .LBB0_505
	s_add_i32 s43, s43, s42
	s_mov_b64 s[2:3], 0
	s_waitcnt vmcnt(4)
	v_mov_b32_e32 v66, v31
	v_mov_b32_e32 v67, v30
	v_mov_b32_e32 v68, v29
	v_mov_b32_e32 v69, v28
	s_branch .LBB0_505

.LBB0_659:
	v_cvt_f32_u32_e32 v1, s46
	s_sub_i32 s34, 0, s46
	s_abs_i32 s3, s42
	s_ashr_i32 s2, s42, 31
	v_rcp_iflag_f32_e32 v1, v1
	v_ashrrev_i32_e32 v61, 3, v0
	v_lshlrev_b32_e32 v0, 3, v0
	v_and_b32_e32 v60, 56, v0
	v_mul_f32_e32 v1, 0x4f7ffffe, v1
	v_cvt_u32_f32_e32 v1, v1
	v_lshlrev_b32_e32 v128, 2, v60
	v_lshlrev_b32_e32 v33, 8, v61
	v_mul_u32_u24_e32 v34, 0x104, v60
	v_readfirstlane_b32 s35, v1
	s_mul_i32 s34, s34, s35
	s_mul_hi_u32 s34, s35, s34
	s_add_i32 s35, s35, s34
	s_mul_hi_u32 s34, s3, s35
	s_mul_i32 s35, s34, s46
	s_sub_i32 s3, s3, s35
	s_add_i32 s40, s34, 1
	s_sub_i32 s35, s3, s46
	s_cmp_ge_u32 s3, s46
	s_cselect_b32 s34, s40, s34
	s_cselect_b32 s3, s35, s3
	s_add_i32 s35, s34, 1
	s_cmp_ge_u32 s3, s46
	s_cselect_b32 s3, s35, s34
	s_xor_b32 s3, s3, s2
	s_sub_i32 s52, s3, s2
	s_mul_i32 s2, s52, s46
	v_lshl_add_u32 v0, s52, 6, v61
	s_sub_i32 s53, s42, s2
	v_ashrrev_i32_e32 v3, 31, v0
	v_mad_u64_u32 v[0:1], s[2:3], v0, s44, 0
	v_mov_b32_e32 v2, v1
	v_mad_u64_u32 v[2:3], s[2:3], v3, s44, v[2:3]
	v_mov_b32_e32 v1, v2
	s_lshl_b32 s2, s53, 8
	v_lshl_add_u64 v[0:1], v[0:1], 2, s[0:1]
	s_ashr_i32 s3, s2, 31
	v_lshl_add_u64 v[0:1], s[2:3], 2, v[0:1]
	v_lshl_add_u64 v[24:25], v[0:1], 0, v[128:129]
	global_load_dwordx4 v[0:3], v[24:25], off nt
	global_load_dwordx4 v[4:7], v[24:25], off offset:16 nt
	global_load_dwordx4 v[8:11], v[24:25], off offset:768 nt
	global_load_dwordx4 v[28:31], v[24:25], off offset:784 nt
	global_load_dwordx4 v[12:15], v[24:25], off offset:256 nt
	global_load_dwordx4 v[16:19], v[24:25], off offset:272 nt
	global_load_dwordx4 v[20:23], v[24:25], off offset:512 nt
	s_nop 0
	global_load_dwordx4 v[24:27], v[24:25], off offset:528 nt
	s_movk_i32 s2, 0x104
	v_mul_lo_u32 v32, v61, s2
	v_sub_u32_e32 v33, v32, v33
	v_readlane_b32 s46, v254, 63
	v_readlane_b32 s47, v254, 0
	v_add_u32_e32 v62, v32, v128
	v_add_u32_e32 v63, v33, v34
	v_lshlrev_b32_e32 v128, 1, v60
	s_waitcnt vmcnt(4)
	v_mov_b32_e32 v67, v28
	v_mov_b32_e32 v66, v29
	v_mov_b32_e32 v65, v30
	v_mov_b32_e32 v64, v31
	s_waitcnt vmcnt(0)
	s_branch .LBB0_661

.LBB0_672:
	s_mov_b32 s50, s2
	s_mov_b32 s2, 0xc001814
	s_mov_b32 s3, 0xffff10
	s_cmp_eq_u32 s50, 1
	s_cselect_b32 s2, 0xd011915, s2
	s_cselect_b32 s3, 0xffff11, s3
	s_cmp_eq_u32 s50, 2
	s_cselect_b32 s2, 0x8041a16, s2
	s_cselect_b32 s3, 0x120f0e, s3
	s_cmp_eq_u32 s50, 3
	s_cselect_b32 s2, 0x13051b17, s2
	s_cselect_b32 s3, 0xffffff, s3
	s_movk_i32 s59, 0x180
	s_bfe_u32 s55, s2, 0x80000
	s_lshr_b32 s58, s55, 2
	s_cmp_lt_i32 s58, 1
	s_cbranch_scc1 .LBB0_677
	s_cmp_eq_u32 s58, 1
	s_mov_b64 s[50:51], -1
	s_cbranch_scc1 .LBB0_675
	s_and_b32 s50, s55, 0xf8
	s_cmp_eq_u32 s58, 4
	s_movk_i32 s51, 0x400
	s_cselect_b32 s51, 0x100, s51
	s_cmp_lg_u32 s50, 8
	s_cselect_b32 s59, s51, 0x80
	s_mov_b64 s[50:51], 0

.LBB0_677:
	s_cmp_lt_i32 s54, s59
	s_cselect_b64 s[50:51], -1, 0
	s_and_b64 vcc, exec, s[50:51]
	s_cselect_b32 s50, 0, s59
	s_sub_i32 s54, s54, s50
	s_cbranch_vccnz .LBB0_685
	s_movk_i32 s59, 0x180
	s_bfe_u32 s58, s2, 0x80008
	s_lshr_b32 s55, s58, 2
	s_cmp_lt_i32 s55, 1
	s_cbranch_scc1 .LBB0_683
	s_cmp_lg_u32 s55, 1
	s_mov_b64 s[50:51], -1
	s_cbranch_scc0 .LBB0_681
	s_and_b32 s50, s58, 0xf8
	s_cmp_eq_u32 s55, 4
	s_movk_i32 s51, 0x400
	s_cselect_b32 s51, 0x100, s51
	s_cmp_lg_u32 s50, 8
	s_cselect_b32 s59, s51, 0x80
	s_mov_b64 s[50:51], 0

.LBB0_686:
	s_movk_i32 s60, 0x180
	s_bfe_u32 s59, s2, 0x80010
	s_lshr_b32 s58, s59, 2
	s_cmp_lt_i32 s58, 1
	s_cbranch_scc1 .LBB0_691
	s_cmp_lg_u32 s58, 1
	s_mov_b64 s[50:51], -1
	s_cbranch_scc0 .LBB0_689
	s_and_b32 s50, s59, 0xf8
	s_cmp_eq_u32 s58, 4
	s_movk_i32 s51, 0x400
	s_cselect_b32 s51, 0x100, s51
	s_cmp_lg_u32 s50, 8
	s_cselect_b32 s60, s51, 0x80
	s_mov_b64 s[50:51], 0

.LBB0_692:
	s_movk_i32 s60, 0x180
	s_bfe_u32 s59, s2, 0x80018
	s_lshr_b32 s58, s59, 2
	s_cmp_lt_i32 s58, 1
	s_cbranch_scc1 .LBB0_697
	s_cmp_lg_u32 s58, 1
	s_mov_b64 s[50:51], -1
	s_cbranch_scc0 .LBB0_695
	s_and_b32 s50, s59, 0xf8
	s_cmp_eq_u32 s58, 4
	s_movk_i32 s51, 0x400
	s_cselect_b32 s51, 0x100, s51
	s_cmp_lg_u32 s50, 8
	s_cselect_b32 s60, s51, 0x80
	s_mov_b64 s[50:51], 0

.LBB0_698:
	s_cmp_gt_i32 s58, -1
	s_cselect_b64 s[50:51], -1, 0
	s_xor_b64 s[42:43], s[42:43], -1
	s_or_b64 s[42:43], s[42:43], s[50:51]
	s_and_b64 vcc, exec, s[42:43]
	s_cbranch_vccnz .LBB0_705
	s_movk_i32 s59, 0x180
	s_bfe_u32 s51, s3, 0x80000
	s_lshr_b32 s50, s51, 2
	s_cmp_lt_i32 s50, 1
	s_cbranch_scc1 .LBB0_704
	s_cmp_lg_u32 s50, 1
	s_mov_b64 s[42:43], -1
	s_cbranch_scc0 .LBB0_702
	s_and_b32 s42, s51, 0xf8
	s_cmp_eq_u32 s50, 4
	s_movk_i32 s43, 0x400
	s_cselect_b32 s43, 0x100, s43
	s_cmp_lg_u32 s42, 8
	s_cselect_b32 s59, s43, 0x80
	s_mov_b64 s[42:43], 0

.LBB0_705:
	s_cmp_gt_i32 s58, -1
	s_cselect_b64 s[42:43], -1, 0
	s_xor_b64 s[34:35], s[34:35], -1
	s_or_b64 s[42:43], s[34:35], s[42:43]
	s_and_b64 vcc, exec, s[42:43]
	s_cbranch_vccnz .LBB0_712
	s_movk_i32 s59, 0x180
	s_bfe_u32 s51, s3, 0x80008
	s_lshr_b32 s50, s51, 2
	s_cmp_lt_i32 s50, 1
	s_cbranch_scc1 .LBB0_711
	s_cmp_lg_u32 s50, 1
	s_mov_b64 s[42:43], -1
	s_cbranch_scc0 .LBB0_709
	s_and_b32 s42, s51, 0xf8
	s_cmp_eq_u32 s50, 4
	s_movk_i32 s43, 0x400
	s_cselect_b32 s43, 0x100, s43
	s_cmp_lg_u32 s42, 8
	s_cselect_b32 s59, s43, 0x80
	s_mov_b64 s[42:43], 0

.LBB0_712:
	s_cmp_gt_i32 s58, -1
	s_cselect_b64 s[42:43], -1, 0
	s_or_b64 s[34:35], s[34:35], s[42:43]
	s_and_b64 vcc, exec, s[34:35]
	s_cbranch_vccnz .LBB0_719
	s_movk_i32 s42, 0x180
	s_bfe_u32 s35, s3, 0x80010
	s_lshr_b32 s34, s35, 2
	s_cmp_lt_i32 s34, 1
	s_cbranch_scc1 .LBB0_718
	s_cmp_lg_u32 s34, 1
	s_mov_b64 s[2:3], -1
	s_cbranch_scc0 .LBB0_716
	s_and_b32 s2, s35, 0xf8
	s_cmp_eq_u32 s34, 4
	s_movk_i32 s3, 0x400
	s_cselect_b32 s3, 0x100, s3
	s_cmp_lg_u32 s2, 8
	s_cselect_b32 s42, s3, 0x80
	s_mov_b64 s[2:3], 0

.LBB0_742:
	s_barrier
	ds_write2_b32 v62, v0, v1 offset1:1
	ds_write2_b32 v62, v2, v3 offset0:2 offset1:3
	ds_write2_b32 v62, v4, v5 offset0:4 offset1:5
	ds_write2_b32 v62, v6, v7 offset0:6 offset1:7
	v_add_u32_e32 v0, 0x4100, v62
	ds_write2_b32 v0, v12, v13 offset1:1
	v_add_u32_e32 v0, 0x4108, v62
	ds_write2_b32 v0, v14, v15 offset1:1
	v_add_u32_e32 v0, 0x4110, v62
	ds_write2_b32 v0, v16, v17 offset1:1
	v_add_u32_e32 v0, 0x4118, v62
	ds_write2_b32 v0, v18, v19 offset1:1
	v_add_u32_e32 v0, 0x8200, v62
	ds_write2_b32 v0, v20, v21 offset1:1
	v_add_u32_e32 v0, 0x8208, v62
	ds_write2_b32 v0, v22, v23 offset1:1
	v_add_u32_e32 v0, 0x8210, v62
	ds_write2_b32 v0, v24, v25 offset1:1
	v_add_u32_e32 v0, 0x8218, v62
	ds_write2_b32 v0, v26, v27 offset1:1
	v_add_u32_e32 v0, 0xc300, v62
	ds_write2_b32 v0, v8, v9 offset1:1
	v_add_u32_e32 v0, 0xc308, v62
	ds_write2_b32 v0, v10, v11 offset1:1
	v_add_u32_e32 v0, 0xc310, v62
	ds_write2_b32 v0, v67, v66 offset1:1
	v_add_u32_e32 v0, 0xc318, v62
	ds_write2_b32 v0, v65, v64 offset1:1
	s_waitcnt lgkmcnt(0)
	s_barrier
	s_lshl_b32 s2, s52, 6
	ds_read2_b32 v[0:1], v63 offset1:65
	ds_read2_b32 v[2:3], v63 offset0:130 offset1:195
	v_add_u32_e32 v6, 0x400, v63
	s_ashr_i32 s3, s2, 31
	ds_read2_b32 v[4:5], v6 offset0:4 offset1:69
	ds_read2_b32 v[6:7], v6 offset0:134 offset1:199
	s_lshl_b64 s[2:3], s[2:3], 1
	s_add_u32 s2, s4, s2
	v_lshl_add_u32 v10, s53, 8, v61
	s_addc_u32 s3, s5, s3
	v_lshl_add_u64 v[8:9], s[2:3], 0, v[128:129]
	s_waitcnt lgkmcnt(3)
	v_cvt_pk_bf16_f32 v0, v0, v1
	s_waitcnt lgkmcnt(2)
	v_cvt_pk_bf16_f32 v1, v2, v3
	s_waitcnt lgkmcnt(1)
	v_cvt_pk_bf16_f32 v2, v4, v5
	v_mad_i64_i32 v[4:5], s[2:3], v10, s45, 0
	v_lshl_add_u64 v[4:5], v[4:5], 1, v[8:9]
	s_waitcnt lgkmcnt(0)
	v_cvt_pk_bf16_f32 v3, v6, v7
	v_add_u32_e32 v6, 0x4600, v63
	global_store_dwordx4 v[4:5], v[0:3], off sc1
	s_nop 1
	v_add_u32_e32 v0, 0x4000, v63
	v_add_u32_e32 v2, 0x4200, v63
	v_add_u32_e32 v4, 0x4400, v63
	ds_read2_b32 v[0:1], v0 offset0:64 offset1:129
	ds_read2_b32 v[2:3], v2 offset0:66 offset1:131
	ds_read2_b32 v[4:5], v4 offset0:68 offset1:133
	s_waitcnt lgkmcnt(2)
	v_cvt_pk_bf16_f32 v0, v0, v1
	s_waitcnt lgkmcnt(1)
	v_cvt_pk_bf16_f32 v1, v2, v3
	s_waitcnt lgkmcnt(0)
	v_cvt_pk_bf16_f32 v2, v4, v5
	v_add_u32_e32 v4, 64, v10
	v_mad_i64_i32 v[4:5], s[2:3], v4, s45, 0
	v_lshl_add_u64 v[4:5], v[4:5], 1, v[8:9]
	ds_read2_b32 v[6:7], v6 offset0:70 offset1:135
	s_waitcnt lgkmcnt(0)
	v_cvt_pk_bf16_f32 v3, v6, v7
	v_add_u32_e32 v6, 0x8800, v63
	global_store_dwordx4 v[4:5], v[0:3], off sc1
	s_nop 1
	v_add_u32_e32 v0, 0x8000, v63
	v_add_u32_e32 v4, 0x8400, v63
	ds_read2_b32 v[0:1], v0 offset0:128 offset1:193
	ds_read2_b32 v[2:3], v4 offset0:2 offset1:67
	ds_read2_b32 v[4:5], v4 offset0:132 offset1:197
	s_waitcnt lgkmcnt(2)
	v_cvt_pk_bf16_f32 v0, v0, v1
	s_waitcnt lgkmcnt(1)
	v_cvt_pk_bf16_f32 v1, v2, v3
	s_waitcnt lgkmcnt(0)
	v_cvt_pk_bf16_f32 v2, v4, v5
	v_add_u32_e32 v4, 0x80, v10
	v_mad_i64_i32 v[4:5], s[2:3], v4, s45, 0
	v_lshl_add_u64 v[4:5], v[4:5], 1, v[8:9]
	ds_read2_b32 v[6:7], v6 offset0:6 offset1:71
	s_waitcnt lgkmcnt(0)
	v_cvt_pk_bf16_f32 v3, v6, v7
	v_add_u32_e32 v6, 0xc800, v63
	global_store_dwordx4 v[4:5], v[0:3], off sc1
	s_nop 1
	v_add_u32_e32 v0, 0xc200, v63
	v_add_u32_e32 v2, 0xc400, v63
	v_add_u32_e32 v4, 0xc600, v63
	ds_read2_b32 v[0:1], v0 offset0:64 offset1:129
	ds_read2_b32 v[2:3], v2 offset0:66 offset1:131
	ds_read2_b32 v[4:5], v4 offset0:68 offset1:133
	s_waitcnt lgkmcnt(2)
	v_cvt_pk_bf16_f32 v0, v0, v1
	s_waitcnt lgkmcnt(1)
	v_cvt_pk_bf16_f32 v1, v2, v3
	s_waitcnt lgkmcnt(0)
	v_cvt_pk_bf16_f32 v2, v4, v5
	v_add_u32_e32 v4, 0xc0, v10
	v_mad_i64_i32 v[4:5], s[2:3], v4, s45, 0
	ds_read2_b32 v[6:7], v6 offset0:70 offset1:135
	s_waitcnt lgkmcnt(0)
	v_cvt_pk_bf16_f32 v3, v6, v7
	v_lshl_add_u64 v[4:5], v[4:5], 1, v[8:9]
	global_store_dwordx4 v[4:5], v[0:3], off sc1
	s_nop 1
	s_andn2_b64 vcc, exec, s[40:41]
	s_mov_b64 s[2:3], -1
	s_cbranch_vccnz .LBB0_660
	s_add_i32 s46, s46, s6
	s_mov_b64 s[2:3], 0
	s_waitcnt vmcnt(4)
	v_mov_b32_e32 v64, v31
	v_mov_b32_e32 v65, v30
	v_mov_b32_e32 v66, v29
	v_mov_b32_e32 v67, v28
	s_branch .LBB0_660
